# static s_setprio 1 for waves 0-3 extended to the cross-attention phase (P9), reset before the next GEMM phase
# baseline (speedup 1.0000x reference)
.LBB0_1292:
	s_waitcnt vmcnt(0)
	s_barrier
.LBB0_1293:
	s_cmp_lt_u32 s73, 4
	s_cbranch_scc0 .Lmy_prio_b
	s_setprio 1
.Lmy_prio_b:
	s_cmp_lt_i32 s74, 10
	s_cselect_b64 s[0:1], -1, 0
	s_cmp_gt_i32 s75, 9
	s_cselect_b64 s[4:5], -1, 0
	s_and_b64 s[4:5], s[0:1], s[4:5]
	s_andn2_b64 vcc, exec, s[4:5]
	s_cbranch_vccnz .LBB0_1309
	v_mbcnt_lo_u32_b32 v0, -1, 0
	v_mbcnt_hi_u32_b32 v3, -1, v0
	s_and_b32 s0, s78, 0xffffffc0
	v_add_u32_e32 v0, s0, v3
	v_ashrrev_i32_e32 v1, 4, v0
	v_lshlrev_b32_e32 v2, 4, v0
	s_movk_i32 s0, 0x110
	v_and_b32_e32 v4, 0x1f0, v2
	v_mul_lo_u32 v5, v1, s0
	v_ashrrev_i32_e32 v6, 5, v0
	s_movk_i32 s0, 0x210
	v_and_b32_e32 v9, 0xf0, v2
	v_lshl_or_b32 v0, v6, 9, v4
	v_mul_lo_u32 v4, v6, s0
	v_and_b32_e32 v2, 0x1e0, v2
	s_add_i32 s0, 0, 0x11000
	v_add3_u32 v12, s0, v4, v2
	v_lshrrev_b32_e32 v4, 1, v3
	s_add_i32 s0, 0, 0x250a8
	v_add_u32_e32 v10, 0, v5
	v_lshlrev_b32_e32 v5, 3, v3
	v_and_b32_e32 v13, 48, v4
	v_mov_b32_e32 v4, s0
	v_and_b32_e32 v11, 8, v5
	ds_read_b64 v[4:5], v4
	s_ashr_i32 s13, s2, 31
	v_and_b32_e32 v7, 31, v3
	v_lshl_or_b32 v130, v1, 10, v9
	v_mov_b32_e32 v1, 0
	s_waitcnt lgkmcnt(0)
	v_readfirstlane_b32 s0, v4
	v_readfirstlane_b32 s1, v5
	s_add_u32 s14, s0, 0x6a00000
	s_addc_u32 s15, s1, 0
	s_add_u32 s6, s0, 0xf000000
	s_addc_u32 s7, s1, 0
	v_lshrrev_b32_e32 v2, 2, v3
	v_cmp_gt_u32_e32 vcc, 32, v3
	s_add_u32 s8, s0, 0x11000000
	s_waitcnt vmcnt(0)
	v_and_b32_e32 v2, 24, v2
	v_mul_u32_u24_e32 v14, 0x210, v7
	v_cndmask_b32_e64 v6, 8, 0, vcc
	v_cndmask_b32_e64 v8, 24, 16, vcc
	s_addc_u32 s9, s1, 0
	v_lshl_add_u64 v[4:5], s[0:1], 0, v[0:1]
	s_mov_b64 s[0:1], 0x6b00000
	v_mul_u32_u24_e32 v0, 0x110, v7
	s_waitcnt vmcnt(0)
	v_add_u32_e32 v150, v12, v11
	s_mov_b32 s12, 0
	v_mov_b32_e32 v131, v1
	v_lshl_or_b32 v146, s73, 5, v7
	v_lshl_add_u64 v[132:133], v[4:5], 0, s[0:1]
	v_add3_u32 v147, v14, v13, 0
	v_add3_u32 v148, v0, v13, 0
	v_mov_b64_e32 v[134:135], 0x100
	v_mov_b64_e32 v[136:137], 0xff
	s_mov_b32 s16, 0x8000
	s_mov_b32 s17, 0x10000
	s_mov_b32 s18, 0x18000
	s_mov_b32 s19, 0x20000
	s_mov_b32 s20, 0x28000
	s_mov_b32 s21, 0x30000
	s_mov_b32 s22, 0x38000
	s_movk_i32 s23, 0x2000
	s_movk_i32 s24, 0x4000
	s_movk_i32 s25, 0x6000
	s_mov_b32 s26, 0xa000
	s_mov_b32 s27, 0xc000
	s_mov_b32 s28, 0xe000
	v_add_u32_e32 v149, v10, v9
	v_lshlrev_b32_e32 v138, 1, v2
	s_mov_b32 s29, 0xff800000
	v_lshlrev_b32_e32 v140, 1, v6
	v_lshlrev_b32_e32 v142, 1, v8
	v_add_u32_e32 v151, 0x2000, v150
	v_add_u32_e32 v152, 0x4000, v150
	v_add_u32_e32 v153, 0x6000, v150
	v_add_u32_e32 v154, 0x8000, v150
	v_add_u32_e32 v155, 0xa000, v150
	v_add_u32_e32 v156, 0xc000, v150
	v_add_u32_e32 v157, 0xe000, v150
	s_barrier
	s_branch .LBB0_1297

.LBB0_1363:
	s_setprio 0
	s_cmp_lt_i32 s74, 11
	s_cselect_b64 s[4:5], -1, 0
	s_and_b64 s[6:7], s[4:5], s[0:1]
	s_andn2_b64 vcc, exec, s[6:7]
	s_cbranch_vccnz .LBB0_1402
	s_and_b32 s4, s78, 0xffffffc0
	s_cmpk_lt_i32 s2, 0x400
	s_cselect_b64 s[0:1], -1, 0
	s_add_i32 s5, 0, 0x250a8
	v_mov_b32_e32 v0, s5
	ds_read_b64 v[2:3], v0
	v_mbcnt_lo_u32_b32 v0, -1, 0
	v_mbcnt_hi_u32_b32 v8, -1, v0
	v_add_u32_e32 v0, s4, v8
	s_and_b64 vcc, exec, s[0:1]
	s_waitcnt lgkmcnt(0)
	v_readfirstlane_b32 s5, v3
	v_readfirstlane_b32 s12, v2
	v_readfirstlane_b32 s4, v0
	s_cbranch_vccz .LBB0_1366
	s_ashr_i32 s8, s2, 31
	s_lshr_b32 s8, s8, 29
	s_add_i32 s8, s2, s8
	s_and_b32 s9, s8, -8
	s_sub_i32 s9, s2, s9
	s_lshl_b32 s11, s9, 7
	s_ashr_i32 s8, s8, 3
	s_mul_i32 s10, s9, 0x81
	s_cmp_lt_i32 s9, 0
	s_cselect_b32 s9, s10, s11
	s_add_i32 s8, s9, s8
	s_ashr_i32 s9, s8, 31
	s_lshr_b32 s9, s9, 26
	s_add_i32 s9, s8, s9
	s_ashr_i32 s10, s9, 6
	s_andn2_b32 s9, s9, 63
	s_sub_i32 s8, s8, s9
	s_bfe_i32 s9, s8, 0x80000
	s_bfe_u32 s9, s9, 0x3000c
	s_add_i32 s9, s8, s9
	s_bfe_i32 s11, s9, 0x80000
	s_and_b32 s9, s9, 0xf8
	s_sub_i32 s8, s8, s9
	s_lshl_b32 s10, s10, 3
	s_sext_i32_i16 s11, s11
	s_sext_i32_i8 s8, s8
	s_add_i32 s42, s10, s8
	s_ashr_i32 s40, s11, 3
